# nt on retout Q-fragment loads and bias2 W1 row loads
# baseline (speedup 1.0000x reference)
.LBB0_351:
	s_add_i32 s46, s42, s16
	s_cmpk_gt_i32 s46, 0xfff
	s_cselect_b64 s[48:49], -1, 0
	s_ashr_i32 s43, s42, 31
	s_lshl_b64 s[66:67], s[42:43], 11
	v_lshl_add_u64 v[64:65], v[110:111], 0, s[66:67]
	s_waitcnt lgkmcnt(0)
	global_load_dwordx4 v[124:127], v[64:65], off nt
	global_load_dwordx4 v[68:71], v[64:65], off offset:1024 nt
	s_cmpk_lt_i32 s46, 0x1000
	s_cselect_b32 s66, s46, s42
	s_ashr_i32 s67, s66, 31
	s_lshl_b64 s[66:67], s[66:67], 11
	v_lshl_add_u64 v[64:65], v[110:111], 0, s[66:67]
	global_load_dwordx4 v[128:131], v[64:65], off nt
	s_nop 0
	global_load_dwordx4 v[64:67], v[64:65], off offset:1024 nt
	s_waitcnt vmcnt(3)
	v_and_b32_e32 v140, 0xffff0000, v124
	v_lshlrev_b32_e32 v132, 16, v125
	v_and_b32_e32 v134, 0xffff0000, v125
	v_lshlrev_b32_e32 v125, 16, v124
	s_waitcnt vmcnt(2)
	v_and_b32_e32 v142, 0xffff0000, v68
	v_mul_f32_e32 v29, v49, v140
	v_and_b32_e32 v141, 16, v124
	v_lshlrev_b32_e32 v145, 16, v68
	v_mov_b32_e32 v124, v140
	v_mul_f32_e32 v137, v57, v142
	v_fmac_f32_e32 v29, v48, v125
	v_lshlrev_b32_e32 v136, 16, v126
	v_and_b32_e32 v118, 0xffff0000, v126
	v_lshlrev_b32_e32 v126, 16, v69
	v_lshlrev_b32_e32 v116, 16, v70
	v_and_b32_e32 v143, 16, v68
	v_and_b32_e32 v68, 0xffff0000, v70
	v_mul_f32_e32 v70, v33, v140
	v_pk_mov_b32 v[140:141], v[124:125], v[140:141] op_sel:[1,0]
	v_fmac_f32_e32 v137, v56, v145
	v_fmac_f32_e32 v29, v50, v132
	v_and_b32_e32 v138, 0xffff0000, v69
	v_pk_mul_f32 v[140:141], v[30:31], v[140:141]
	v_fmac_f32_e32 v137, v58, v126
	v_fmac_f32_e32 v29, v51, v134
	v_mov_b32_e32 v144, v142
	v_fmac_f32_e32 v70, v32, v125
	v_pk_fma_f32 v[124:125], v[102:103], v[124:125], v[140:141]
	v_fmac_f32_e32 v137, v59, v138
	v_fmac_f32_e32 v29, v52, v136
	v_lshlrev_b32_e32 v146, 16, v127
	v_mul_f32_e32 v139, v41, v142
	v_pk_mov_b32 v[142:143], v[144:145], v[142:143] op_sel:[1,0]
	v_fmac_f32_e32 v70, v34, v132
	s_waitcnt vmcnt(1)
	v_lshlrev_b32_e32 v135, 16, v128
	v_pk_fma_f32 v[124:125], v[100:101], v[132:133], v[124:125] op_sel_hi:[1,0,1]
	v_fmac_f32_e32 v137, v60, v116
	v_fmac_f32_e32 v29, v53, v118
	v_and_b32_e32 v112, 0xffff0000, v127
	v_lshlrev_b32_e32 v114, 16, v71
	v_pk_mul_f32 v[142:143], v[108:109], v[142:143]
	v_fmac_f32_e32 v70, v35, v134
	v_pk_fma_f32 v[124:125], v[98:99], v[134:135], v[124:125] op_sel_hi:[1,0,1]
	v_fmac_f32_e32 v137, v61, v68
	v_fmac_f32_e32 v29, v54, v146
	v_pk_fma_f32 v[140:141], v[92:93], v[144:145], v[142:143]
	v_lshlrev_b32_e32 v143, 16, v129
	v_and_b32_e32 v142, 0xffff0000, v128
	v_fmac_f32_e32 v70, v36, v136
	v_pk_fma_f32 v[124:125], v[96:97], v[136:137], v[124:125] op_sel_hi:[1,0,1]
	v_fmac_f32_e32 v29, v55, v112
	v_fmac_f32_e32 v137, v62, v114
	v_and_b32_e32 v136, 0xffff0000, v71
	v_fmac_f32_e32 v139, v40, v145
	v_pk_mul_f32 v[132:133], v[106:107], v[142:143]
	v_add_f32_e32 v29, 0, v29
	v_fmac_f32_e32 v137, v63, v136
	v_fmac_f32_e32 v139, v42, v126
	s_waitcnt vmcnt(0)
	v_lshlrev_b32_e32 v145, 16, v66
	v_and_b32_e32 v69, 0xffff0000, v66
	v_lshlrev_b32_e32 v127, 16, v130
	v_fma_f32 v66, v28, v135, v132
	v_add_f32_e32 v29, v29, v137
	v_fmac_f32_e32 v139, v43, v138
	v_and_b32_e32 v144, 0xffff0000, v130
	v_lshlrev_b32_e32 v147, 16, v131
	v_and_b32_e32 v113, 0xffff0000, v131
	v_pk_fma_f32 v[130:131], v[90:91], v[126:127], v[140:141] op_sel_hi:[1,0,1]
	v_mul_f32_e32 v140, v49, v142
	v_mul_f32_e32 v141, v33, v142
	v_mul_f32_e32 v148, v25, v142
	v_add_f32_e32 v66, v133, v66
	v_lshlrev_b32_e32 v132, 16, v64
	v_and_b32_e32 v133, 0xffff0000, v64
	ds_bpermute_b32 v64, v117, v29
	v_fmac_f32_e32 v139, v44, v116
	v_fmac_f32_e32 v70, v37, v118
	v_fmac_f32_e32 v140, v48, v135
	v_fmac_f32_e32 v141, v32, v135
	v_fmac_f32_e32 v148, v24, v135
	v_pk_fma_f32 v[130:131], v[88:89], v[138:139], v[130:131] op_sel_hi:[1,0,1]
	v_fmac_f32_e32 v139, v45, v68
	v_fmac_f32_e32 v70, v38, v146
	v_fmac_f32_e32 v140, v50, v143
	v_fmac_f32_e32 v141, v34, v143
	v_fmac_f32_e32 v148, v26, v143
	v_and_b32_e32 v126, 0xffff0000, v129
	v_fmac_f32_e32 v140, v51, v126
	v_fmac_f32_e32 v141, v35, v126
	v_fmac_f32_e32 v148, v27, v126
	v_fmac_f32_e32 v70, v39, v112
	v_fmac_f32_e32 v139, v46, v114
	v_fmac_f32_e32 v140, v52, v127
	v_fmac_f32_e32 v141, v36, v127
	v_fmac_f32_e32 v148, v8, v127
	v_pk_mul_f32 v[126:127], v[104:105], v[126:127]
	v_and_b32_e32 v135, 0xffff0000, v65
	v_lshlrev_b32_e32 v134, 16, v65
	v_add_f32_e32 v65, 0, v70
	v_fmac_f32_e32 v139, v47, v136
	v_add_f32_e32 v66, v126, v66
	s_waitcnt lgkmcnt(0)
	v_add_f32_e32 v29, v29, v64
	v_add_f32_e32 v65, v65, v139
	v_add_f32_e32 v127, v127, v66
	ds_bpermute_b32 v64, v119, v29
	ds_bpermute_b32 v66, v117, v65
	v_mul_f32_e32 v138, v57, v133
	v_mul_f32_e32 v142, v41, v133
	v_mul_f32_e32 v143, v17, v133
	s_waitcnt lgkmcnt(1)
	v_add_f32_e32 v29, v29, v64
	s_waitcnt lgkmcnt(0)
	v_add_f32_e32 v65, v65, v66
	ds_bpermute_b32 v70, v120, v29
	ds_bpermute_b32 v66, v119, v65
	v_fmac_f32_e32 v138, v56, v132
	v_fmac_f32_e32 v142, v40, v132
	v_fmac_f32_e32 v143, v16, v132
	s_waitcnt lgkmcnt(1)
	v_add_f32_e32 v29, v29, v70
	s_waitcnt lgkmcnt(0)
	v_add_f32_e32 v66, v65, v66
	ds_bpermute_b32 v70, v121, v29
	ds_bpermute_b32 v71, v120, v66
	v_pk_mul_f32 v[132:133], v[20:21], v[132:133]
	v_lshlrev_b32_e32 v115, 16, v67
	v_add_f32_e32 v64, v132, v133
	v_fmac_f32_e32 v64, v22, v134
	s_waitcnt lgkmcnt(1)
	v_add_f32_e32 v29, v29, v70
	s_waitcnt lgkmcnt(0)
	v_add_f32_e32 v70, v66, v71
	v_pk_fma_f32 v[64:65], v[22:23], v[134:135], v[64:65] op_sel_hi:[1,1,0]
	ds_bpermute_b32 v126, v121, v70
	ds_bpermute_b32 v64, v122, v29
	v_mul_f32_e32 v129, v1, v144
	v_fmac_f32_e32 v138, v58, v134
	v_fmac_f32_e32 v142, v42, v134
	v_fmac_f32_e32 v143, v18, v134
	v_and_b32_e32 v137, 0xffff0000, v67
	s_waitcnt lgkmcnt(1)
	v_add_f32_e32 v67, v70, v126
	v_mul_f32_e32 v128, v1, v118
	v_mov_b32_e32 v126, v125
	v_fmac_f32_e32 v138, v59, v135
	v_fmac_f32_e32 v142, v43, v135
	v_fmac_f32_e32 v143, v19, v135
	v_mul_f32_e32 v71, v4, v145
	s_waitcnt lgkmcnt(0)
	v_add_f32_e32 v29, v29, v64
	v_pk_fma_f32 v[132:133], v[0:1], v[118:119], v[124:125] op_sel_hi:[1,0,1]
	v_pk_add_f32 v[124:125], v[128:129], v[126:127]
	v_pk_fma_f32 v[128:129], v[94:95], v[116:117], v[130:131] op_sel_hi:[1,0,1]
	v_mul_f32_e32 v70, v95, v116
	v_mov_b32_e32 v64, v131
	v_fmac_f32_e32 v138, v60, v145
	v_fmac_f32_e32 v142, v44, v145
	v_fmac_f32_e32 v143, v12, v145
	v_pk_fma_f32 v[126:127], v[74:75], v[146:147], v[132:133] op_sel_hi:[1,0,1]
	v_pk_add_f32 v[64:65], v[70:71], v[64:65]
	v_pk_fma_f32 v[70:71], v[80:81], v[68:69], v[128:129] op_sel_hi:[1,0,1]
	v_fmac_f32_e32 v138, v61, v69
	v_fmac_f32_e32 v142, v45, v69
	v_fmac_f32_e32 v143, v13, v69
	v_pk_fma_f32 v[126:127], v[72:73], v[112:113], v[126:127] op_sel_hi:[1,0,1]
	v_pk_fma_f32 v[64:65], v[86:87], v[68:69], v[64:65]
	v_pk_fma_f32 v[68:69], v[78:79], v[114:115], v[70:71] op_sel_hi:[1,0,1]
	v_pk_add_f32 v[126:127], v[126:127], 0 op_sel_hi:[1,0]
	v_pk_fma_f32 v[68:69], v[76:77], v[136:137], v[68:69] op_sel_hi:[1,0,1]
	v_pk_fma_f32 v[124:125], v[2:3], v[146:147], v[124:125]
	v_pk_add_f32 v[68:69], v[126:127], v[68:69]
	ds_bpermute_b32 v70, v117, v68
	ds_bpermute_b32 v71, v117, v69
	v_pk_fma_f32 v[124:125], v[82:83], v[112:113], v[124:125]
	v_pk_fma_f32 v[64:65], v[6:7], v[114:115], v[64:65]
	v_pk_add_f32 v[124:125], v[124:125], 0 op_sel_hi:[1,0]
	v_pk_fma_f32 v[64:65], v[84:85], v[136:137], v[64:65]
	s_waitcnt lgkmcnt(0)
	v_pk_add_f32 v[68:69], v[68:69], v[70:71]
	v_pk_add_f32 v[64:65], v[124:125], v[64:65]
	ds_bpermute_b32 v125, v117, v65
	ds_bpermute_b32 v126, v119, v68
	ds_bpermute_b32 v127, v119, v69
	v_mov_b32_e32 v124, v71
	ds_bpermute_b32 v70, v122, v67
	s_waitcnt lgkmcnt(3)
	v_pk_add_f32 v[64:65], v[64:65], v[124:125]
	ds_bpermute_b32 v71, v119, v65
	s_waitcnt lgkmcnt(2)
	v_pk_add_f32 v[68:69], v[68:69], v[126:127]
	ds_bpermute_b32 v124, v120, v68
	ds_bpermute_b32 v125, v120, v69
	s_waitcnt lgkmcnt(3)
	v_add_f32_e32 v112, v67, v70
	v_mov_b32_e32 v70, v127
	s_waitcnt lgkmcnt(2)
	v_pk_add_f32 v[64:65], v[64:65], v[70:71]
	ds_bpermute_b32 v71, v120, v65
	s_waitcnt lgkmcnt(1)
	v_pk_add_f32 v[68:69], v[68:69], v[124:125]
	ds_bpermute_b32 v127, v121, v69
	ds_bpermute_b32 v126, v121, v68
	v_mov_b32_e32 v70, v125
	s_waitcnt lgkmcnt(2)
	v_pk_add_f32 v[64:65], v[64:65], v[70:71]
	ds_bpermute_b32 v71, v121, v65
	v_fmac_f32_e32 v140, v53, v144
	s_waitcnt lgkmcnt(1)
	v_pk_add_f32 v[68:69], v[68:69], v[126:127]
	ds_bpermute_b32 v125, v122, v69
	ds_bpermute_b32 v124, v122, v68
	v_fmac_f32_e32 v141, v37, v144
	v_fmac_f32_e32 v148, v9, v144
	v_fmac_f32_e32 v140, v54, v147
	v_fmac_f32_e32 v141, v38, v147
	v_fmac_f32_e32 v148, v10, v147
	v_mov_b32_e32 v70, v127
	v_fmac_f32_e32 v140, v55, v113
	v_fmac_f32_e32 v138, v62, v115
	v_fmac_f32_e32 v141, v39, v113
	v_fmac_f32_e32 v142, v46, v115
	v_fmac_f32_e32 v148, v11, v113
	v_fmac_f32_e32 v143, v14, v115
	s_waitcnt lgkmcnt(2)
	v_pk_add_f32 v[64:65], v[64:65], v[70:71]
	s_waitcnt lgkmcnt(0)
	v_pk_add_f32 v[70:71], v[68:69], v[124:125]
	v_add_f32_e32 v116, 0, v140
	v_fmac_f32_e32 v138, v63, v137
	v_add_f32_e32 v124, 0, v141
	v_fmac_f32_e32 v142, v47, v137
	v_add_f32_e32 v113, 0, v148
	v_fmac_f32_e32 v143, v15, v137
	v_add_f32_e32 v116, v116, v138
	v_add_f32_e32 v124, v124, v142
	v_add_f32_e32 v113, v113, v143
	v_mov_b32_e32 v126, v125
	ds_bpermute_b32 v118, v117, v116
	ds_bpermute_b32 v125, v117, v124
	ds_bpermute_b32 v115, v117, v113
	ds_bpermute_b32 v127, v122, v65
	ds_bpermute_b32 v66, v123, v29
	s_waitcnt lgkmcnt(4)
	v_add_f32_e32 v116, v116, v118
	s_waitcnt lgkmcnt(3)
	v_add_f32_e32 v124, v124, v125
	s_waitcnt lgkmcnt(2)
	v_add_f32_e32 v113, v113, v115
	ds_bpermute_b32 v118, v119, v116
	ds_bpermute_b32 v125, v119, v124
	ds_bpermute_b32 v115, v119, v113
	s_waitcnt lgkmcnt(4)
	v_pk_add_f32 v[64:65], v[64:65], v[126:127]
	ds_bpermute_b32 v114, v123, v112
	s_waitcnt lgkmcnt(3)
	v_add_f32_e32 v116, v116, v118
	s_waitcnt lgkmcnt(2)
	v_add_f32_e32 v124, v124, v125
	s_waitcnt lgkmcnt(1)
	v_add_f32_e32 v113, v113, v115
	ds_bpermute_b32 v118, v120, v116
	ds_bpermute_b32 v125, v120, v124
	ds_bpermute_b32 v115, v120, v113
	ds_bpermute_b32 v68, v123, v70
	ds_bpermute_b32 v69, v123, v71
	s_waitcnt lgkmcnt(4)
	v_add_f32_e32 v116, v116, v118
	s_waitcnt lgkmcnt(3)
	v_add_f32_e32 v124, v124, v125
	s_waitcnt lgkmcnt(2)
	v_add_f32_e32 v113, v113, v115
	ds_bpermute_b32 v118, v121, v116
	ds_bpermute_b32 v125, v121, v124
	ds_bpermute_b32 v115, v121, v113
	ds_bpermute_b32 v67, v123, v65
	s_waitcnt lgkmcnt(3)
	v_add_f32_e32 v116, v116, v118
	s_waitcnt lgkmcnt(2)
	v_add_f32_e32 v124, v124, v125
	s_waitcnt lgkmcnt(1)
	v_add_f32_e32 v126, v113, v115
	ds_bpermute_b32 v118, v122, v116
	ds_bpermute_b32 v125, v122, v124
	ds_bpermute_b32 v127, v122, v126
	s_waitcnt lgkmcnt(2)
	v_add_f32_e32 v113, v116, v118
	s_waitcnt lgkmcnt(1)
	v_add_f32_e32 v116, v124, v125
	s_waitcnt lgkmcnt(0)
	v_add_f32_e32 v124, v126, v127
	ds_bpermute_b32 v115, v123, v113
	ds_bpermute_b32 v118, v123, v116
	ds_bpermute_b32 v125, v123, v124
	s_and_saveexec_b64 s[66:67], s[4:5]
	s_cbranch_execz .LBB0_350
	s_lshl_b64 s[68:69], s[42:43], 2
	s_add_u32 s70, s83, s68
	v_add_f32_e32 v112, v112, v114
	v_add_f32_e32 v29, v29, v66
	s_addc_u32 s71, s88, s69
	s_mov_b64 s[72:73], -1
	s_and_b64 vcc, exec, s[48:49]
	global_store_dword v5, v29, s[70:71] sc1
	s_cbranch_vccz .LBB0_354
	s_add_u32 s48, s89, s68
	s_addc_u32 s49, s90, s69
	global_store_dword v5, v112, s[48:49] sc1
	s_mov_b64 s[72:73], 0

.LBB0_376:
	s_lshl_b64 s[4:5], s[60:61], 4
	s_or_b32 s4, s4, s11
	s_lshl_b64 s[6:7], s[4:5], 19
	s_add_u32 s46, s76, s6
	s_addc_u32 s47, s18, s7
	s_add_u32 s16, s59, s6
	s_addc_u32 s17, s82, s7
	s_sub_i32 s6, 11, s62
	s_cmpk_lt_u32 s96, 0x100
	s_cselect_b32 s45, s62, s6
	s_and_b64 s[6:7], s[74:75], exec
	s_cselect_b32 s6, s46, s16
	s_cselect_b32 s7, s47, s17
	s_add_u32 s6, s6, s0
	s_addc_u32 s7, s7, s1
	s_add_i32 s42, 0, 0x10000
	s_add_i32 s14, s42, s33
	s_add_i32 s44, s14, s34
	s_add_i32 s44, s44, s35
	s_barrier
	v_mbcnt_lo_u32_b32 v175, -1, 0
	v_mbcnt_hi_u32_b32 v175, -1, v175
	s_and_b64 s[14:15], s[84:85], exec
	v_lshlrev_b32_e32 v179, 3, v175
	v_add_u32_e32 v0, s77, v179
	s_cselect_b32 s15, s46, s16
	v_ashrrev_i32_e32 v1, 31, v0
	s_cselect_b32 s14, s47, s17
	s_add_u32 s16, s15, s28
	v_lshl_add_u64 v[0:1], v[0:1], 1, s[6:7]
	s_mov_b32 m0, s44
	s_addc_u32 s17, s14, s29
	s_add_i32 s20, s42, s56
	global_load_lds_dwordx4 v[0:1], off nt
	v_add_u32_e32 v0, s78, v179
	s_add_i32 s43, s20, s57
	v_ashrrev_i32_e32 v1, 31, v0
	s_add_i32 s43, s43, s64
	v_lshl_add_u64 v[0:1], v[0:1], 1, s[16:17]
	s_mov_b32 m0, s43
	s_add_u32 s18, s15, s38
	global_load_lds_dwordx4 v[0:1], off nt
	v_add_u32_e32 v0, s79, v179
	s_addc_u32 s19, s14, s39
	s_add_i32 s39, s20, s65
	v_ashrrev_i32_e32 v1, 31, v0
	s_add_i32 s39, s39, s80
	s_add_i32 s15, 0, 0x16000
	v_lshl_add_u64 v[0:1], v[0:1], 1, s[18:19]
	s_mov_b32 m0, s39
	v_add_u32_e32 v2, 0x400, v179
	s_add_i32 s14, s15, s33
	global_load_lds_dwordx4 v[0:1], off nt
	v_add_u32_e32 v0, s77, v2
	s_add_i32 s38, s14, s34
	v_ashrrev_i32_e32 v1, 31, v0
	s_add_i32 s38, s38, s35
	v_lshl_add_u64 v[0:1], v[0:1], 1, s[6:7]
	s_mov_b32 m0, s38
	s_add_i32 s14, s15, s56
	global_load_lds_dwordx4 v[0:1], off nt
	v_add_u32_e32 v0, s78, v2
	s_add_i32 s28, s14, s57
	v_ashrrev_i32_e32 v1, 31, v0
	s_add_i32 s28, s28, s64
	s_add_i32 s29, s14, s65
	v_lshl_add_u64 v[0:1], v[0:1], 1, s[16:17]
	s_mov_b32 m0, s28
	s_add_i32 s29, s29, s80
	s_lshl_b32 s14, s95, 16
	global_load_lds_dwordx4 v[0:1], off nt
	v_add_u32_e32 v0, s79, v2
	s_add_u32 s20, s46, s14
	v_and_b32_e32 v211, 31, v175
	v_ashrrev_i32_e32 v1, 31, v0
	s_addc_u32 s21, s47, 0
	s_lshl_b32 s14, s45, 5
	v_lshl_add_u64 v[0:1], v[0:1], 1, s[18:19]
	s_mov_b32 m0, s29
	v_or_b32_e32 v181, s14, v211
	v_ashrrev_i32_e32 v212, 5, v175
	global_load_lds_dwordx4 v[0:1], off nt
	v_lshlrev_b32_e32 v0, 5, v181
	v_ashrrev_i32_e32 v1, 31, v0
	v_lshlrev_b32_e32 v2, 3, v212
	v_lshl_add_u64 v[0:1], v[0:1], 1, s[20:21]
	v_ashrrev_i32_e32 v3, 31, v2
	v_lshl_add_u64 v[0:1], v[2:3], 1, v[0:1]
	s_movk_i32 s20, 0x4000
	v_add_co_u32_e32 v2, vcc, s20, v0
	s_mov_b32 s20, 0x8000
	s_nop 0
	v_addc_co_u32_e32 v3, vcc, 0, v1, vcc
	global_load_dwordx4 v[128:131], v[0:1], off nt
	global_load_dwordx4 v[132:135], v[0:1], off offset:32 nt
	global_load_dwordx4 v[136:139], v[2:3], off nt
	global_load_dwordx4 v[140:143], v[2:3], off offset:32 nt
	v_add_co_u32_e32 v2, vcc, s20, v0
	s_movk_i32 s20, 0x100
	s_nop 0
	v_addc_co_u32_e32 v3, vcc, 0, v1, vcc
	v_add_co_u32_e32 v0, vcc, 0xc000, v0
	global_load_dwordx4 v[144:147], v[2:3], off nt
	global_load_dwordx4 v[148:151], v[2:3], off offset:32 nt
	v_addc_co_u32_e32 v1, vcc, 0, v1, vcc
	global_load_dwordx4 v[152:155], v[0:1], off nt
	global_load_dwordx4 v[156:159], v[0:1], off offset:32 nt
	v_mbcnt_lo_u32_b32 v0, -1, 0
	v_mbcnt_hi_u32_b32 v0, -1, v0
	s_nop 0
	v_add_u32_e32 v0, s97, v0
	v_cmp_gt_i32_e32 vcc, s20, v0
	s_and_saveexec_b64 s[20:21], vcc
	s_cbranch_execz .LBB0_378
	s_lshl_b32 s11, s11, 11
	v_lshl_add_u32 v40, v0, 3, s11
	v_mul_f32_e32 v0, 0x43800000, v174
	s_mov_b32 s11, 0xc2fc0000
	v_mov_b32_e32 v1, 0x42800000
	v_cmp_gt_f32_e32 vcc, s11, v0
	s_and_b64 s[22:23], vcc, exec
	s_cselect_b32 s11, 0xffffffc0, 0
	v_cndmask_b32_e32 v0, 0, v1, vcc
	v_fmac_f32_e32 v0, 0x43800000, v174
	v_exp_f32_e32 v0, v0
	v_ashrrev_i32_e32 v41, 31, v40
	v_mov_b32_e32 v38, 0
	v_mov_b32_e32 v39, v38
	v_ldexp_f32 v36, v0, s11
	s_ashr_i32 s11, s10, 31
	v_lshl_add_u64 v[0:1], v[40:41], 1, s[8:9]
	s_lshl_b64 s[22:23], s[10:11], 16
	v_lshl_add_u64 v[2:3], v[0:1], 0, s[22:23]
	global_load_dwordx4 v[42:45], v[2:3], off nt
	s_or_b32 s22, s10, 1
	s_ashr_i32 s23, s22, 31
	s_lshl_b64 s[22:23], s[22:23], 16
	v_lshl_add_u64 v[2:3], v[0:1], 0, s[22:23]
	global_load_dwordx4 v[46:49], v[2:3], off nt
	s_or_b32 s22, s10, 2
	s_ashr_i32 s23, s22, 31
	s_lshl_b64 s[22:23], s[22:23], 16
	v_lshl_add_u64 v[2:3], v[0:1], 0, s[22:23]
	s_or_b32 s22, s10, 3
	s_ashr_i32 s23, s22, 31
	s_lshl_b64 s[22:23], s[22:23], 16
	v_lshl_add_u64 v[4:5], v[0:1], 0, s[22:23]
	global_load_dwordx4 v[50:53], v[2:3], off nt
	global_load_dwordx4 v[54:57], v[4:5], off nt
	s_or_b32 s22, s10, 4
	s_ashr_i32 s23, s22, 31
	s_lshl_b64 s[22:23], s[22:23], 16
	v_lshl_add_u64 v[2:3], v[0:1], 0, s[22:23]
	s_or_b32 s22, s10, 5
	s_ashr_i32 s23, s22, 31
	s_lshl_b64 s[22:23], s[22:23], 16
	v_lshl_add_u64 v[4:5], v[0:1], 0, s[22:23]
	global_load_dwordx4 v[58:61], v[2:3], off nt
	global_load_dwordx4 v[62:65], v[4:5], off nt
	s_or_b32 s22, s10, 6
	s_ashr_i32 s23, s22, 31
	s_lshl_b64 s[22:23], s[22:23], 16
	v_lshl_add_u64 v[2:3], v[0:1], 0, s[22:23]
	s_or_b32 s22, s10, 7
	s_ashr_i32 s23, s22, 31
	s_lshl_b64 s[22:23], s[22:23], 16
	v_lshl_add_u64 v[4:5], v[0:1], 0, s[22:23]
	global_load_dwordx4 v[32:35], v[2:3], off nt
	global_load_dwordx4 v[28:31], v[4:5], off nt
	s_or_b32 s22, s10, 8
	s_ashr_i32 s23, s22, 31
	s_lshl_b64 s[22:23], s[22:23], 16
	v_lshl_add_u64 v[2:3], v[0:1], 0, s[22:23]
	s_or_b32 s22, s10, 9
	s_ashr_i32 s23, s22, 31
	s_lshl_b64 s[22:23], s[22:23], 16
	v_lshl_add_u64 v[4:5], v[0:1], 0, s[22:23]
	global_load_dwordx4 v[24:27], v[2:3], off nt
	global_load_dwordx4 v[20:23], v[4:5], off nt
	s_or_b32 s22, s10, 10
	s_ashr_i32 s23, s22, 31
	s_lshl_b64 s[22:23], s[22:23], 16
	v_lshl_add_u64 v[2:3], v[0:1], 0, s[22:23]
	s_or_b32 s22, s10, 11
	s_ashr_i32 s23, s22, 31
	s_lshl_b64 s[22:23], s[22:23], 16
	v_lshl_add_u64 v[4:5], v[0:1], 0, s[22:23]
	global_load_dwordx4 v[16:19], v[2:3], off nt
	global_load_dwordx4 v[12:15], v[4:5], off nt
	s_or_b32 s22, s10, 12
	s_ashr_i32 s23, s22, 31
	s_lshl_b64 s[22:23], s[22:23], 16
	v_lshl_add_u64 v[2:3], v[0:1], 0, s[22:23]
	s_or_b32 s22, s10, 13
	s_ashr_i32 s23, s22, 31
	s_lshl_b64 s[22:23], s[22:23], 16
	v_lshl_add_u64 v[4:5], v[0:1], 0, s[22:23]
	global_load_dwordx4 v[8:11], v[2:3], off nt
	s_nop 0
	global_load_dwordx4 v[4:7], v[4:5], off nt
	s_or_b32 s10, s10, 14
	s_ashr_i32 s11, s10, 31
	s_lshl_b64 s[10:11], s[10:11], 16
	v_lshl_add_u64 v[0:1], v[0:1], 0, s[10:11]
	global_load_dwordx4 v[0:3], v[0:1], off nt
	s_lshl_b32 s22, s81, 20
	s_and_b32 s9, s9, 0xffff
	s_mov_b32 s11, 0x20000
	s_mov_b32 s10, 0x1000000
	v_lshl_add_u32 v37, v40, 1, s22
	v_mov_b32_e32 v40, v38
	v_mov_b32_e32 v41, v38
	buffer_store_dwordx4 v[38:41], v37, s[8:11], 0 offen sc1
	v_add_u32_e32 v70, 0x10000, v37
	s_nop 0
	v_mul_f32_e32 v38, 0, v36
	s_waitcnt vmcnt(0)
	v_lshlrev_b32_e32 v40, 16, v42
	v_and_b32_e32 v41, 0xffff0000, v42
	v_pk_add_f32 v[66:67], v[38:39], v[40:41] op_sel_hi:[0,1]
	v_lshlrev_b32_e32 v40, 16, v43
	v_and_b32_e32 v41, 0xffff0000, v43
	v_pk_add_f32 v[42:43], v[38:39], v[40:41] op_sel_hi:[0,1]
	v_lshlrev_b32_e32 v40, 16, v44
	v_and_b32_e32 v41, 0xffff0000, v44
	v_pk_add_f32 v[68:69], v[38:39], v[40:41] op_sel_hi:[0,1]
	v_lshlrev_b32_e32 v40, 16, v45
	v_and_b32_e32 v41, 0xffff0000, v45
	v_pk_add_f32 v[44:45], v[38:39], v[40:41] op_sel_hi:[0,1]
	v_cvt_pk_bf16_f32 v38, v66, v67
	v_cvt_pk_bf16_f32 v39, v42, v43
	v_cvt_pk_bf16_f32 v40, v68, v69
	v_cvt_pk_bf16_f32 v41, v44, v45
	buffer_store_dwordx4 v[38:41], v70, s[8:11], 0 offen sc1
	s_nop 1
	v_lshlrev_b32_e32 v38, 16, v46
	v_and_b32_e32 v39, 0xffff0000, v46
	v_pk_fma_f32 v[66:67], v[36:37], v[66:67], v[38:39] op_sel_hi:[0,1,1]
	v_lshlrev_b32_e32 v38, 16, v47
	v_and_b32_e32 v39, 0xffff0000, v47
	v_pk_fma_f32 v[42:43], v[36:37], v[42:43], v[38:39] op_sel_hi:[0,1,1]
	v_lshlrev_b32_e32 v38, 16, v48
	v_and_b32_e32 v39, 0xffff0000, v48
	v_pk_fma_f32 v[46:47], v[36:37], v[68:69], v[38:39] op_sel_hi:[0,1,1]
	v_lshlrev_b32_e32 v38, 16, v49
	v_and_b32_e32 v39, 0xffff0000, v49
	v_pk_fma_f32 v[44:45], v[36:37], v[44:45], v[38:39] op_sel_hi:[0,1,1]
	v_add_u32_e32 v48, 0x20000, v37
	v_cvt_pk_bf16_f32 v38, v66, v67
	v_cvt_pk_bf16_f32 v39, v42, v43
	v_cvt_pk_bf16_f32 v40, v46, v47
	v_cvt_pk_bf16_f32 v41, v44, v45
	buffer_store_dwordx4 v[38:41], v48, s[8:11], 0 offen sc1
	s_nop 1
	v_lshlrev_b32_e32 v38, 16, v50
	v_and_b32_e32 v39, 0xffff0000, v50
	v_pk_fma_f32 v[48:49], v[36:37], v[66:67], v[38:39] op_sel_hi:[0,1,1]
	v_lshlrev_b32_e32 v38, 16, v51
	v_and_b32_e32 v39, 0xffff0000, v51
	v_pk_fma_f32 v[42:43], v[36:37], v[42:43], v[38:39] op_sel_hi:[0,1,1]
	v_lshlrev_b32_e32 v38, 16, v52
	v_and_b32_e32 v39, 0xffff0000, v52
	v_pk_fma_f32 v[46:47], v[36:37], v[46:47], v[38:39] op_sel_hi:[0,1,1]
	v_lshlrev_b32_e32 v38, 16, v53
	v_and_b32_e32 v39, 0xffff0000, v53
	v_pk_fma_f32 v[44:45], v[36:37], v[44:45], v[38:39] op_sel_hi:[0,1,1]
	v_add_u32_e32 v50, 0x30000, v37
	v_cvt_pk_bf16_f32 v38, v48, v49
	v_cvt_pk_bf16_f32 v39, v42, v43
	v_cvt_pk_bf16_f32 v40, v46, v47
	v_cvt_pk_bf16_f32 v41, v44, v45
	buffer_store_dwordx4 v[38:41], v50, s[8:11], 0 offen sc1
	v_add_u32_e32 v50, 0x40000, v37
	s_nop 0
	v_lshlrev_b32_e32 v38, 16, v54
	v_and_b32_e32 v39, 0xffff0000, v54
	v_pk_fma_f32 v[48:49], v[36:37], v[48:49], v[38:39] op_sel_hi:[0,1,1]
	v_lshlrev_b32_e32 v38, 16, v55
	v_and_b32_e32 v39, 0xffff0000, v55
	v_pk_fma_f32 v[42:43], v[36:37], v[42:43], v[38:39] op_sel_hi:[0,1,1]
	v_lshlrev_b32_e32 v38, 16, v56
	v_and_b32_e32 v39, 0xffff0000, v56
	v_pk_fma_f32 v[46:47], v[36:37], v[46:47], v[38:39] op_sel_hi:[0,1,1]
	v_lshlrev_b32_e32 v38, 16, v57
	v_and_b32_e32 v39, 0xffff0000, v57
	v_pk_fma_f32 v[44:45], v[36:37], v[44:45], v[38:39] op_sel_hi:[0,1,1]
	v_cvt_pk_bf16_f32 v38, v48, v49
	v_cvt_pk_bf16_f32 v39, v42, v43
	v_cvt_pk_bf16_f32 v40, v46, v47
	v_cvt_pk_bf16_f32 v41, v44, v45
	buffer_store_dwordx4 v[38:41], v50, s[8:11], 0 offen sc1
	v_add_u32_e32 v50, 0x50000, v37
	s_nop 0
	v_lshlrev_b32_e32 v38, 16, v58
	v_and_b32_e32 v39, 0xffff0000, v58
	v_pk_fma_f32 v[48:49], v[36:37], v[48:49], v[38:39] op_sel_hi:[0,1,1]
	v_lshlrev_b32_e32 v38, 16, v59
	v_and_b32_e32 v39, 0xffff0000, v59
	v_pk_fma_f32 v[42:43], v[36:37], v[42:43], v[38:39] op_sel_hi:[0,1,1]
	v_lshlrev_b32_e32 v38, 16, v60
	v_and_b32_e32 v39, 0xffff0000, v60
	v_pk_fma_f32 v[46:47], v[36:37], v[46:47], v[38:39] op_sel_hi:[0,1,1]
	v_lshlrev_b32_e32 v38, 16, v61
	v_and_b32_e32 v39, 0xffff0000, v61
	v_pk_fma_f32 v[44:45], v[36:37], v[44:45], v[38:39] op_sel_hi:[0,1,1]
	v_cvt_pk_bf16_f32 v38, v48, v49
	v_cvt_pk_bf16_f32 v39, v42, v43
	v_cvt_pk_bf16_f32 v40, v46, v47
	v_cvt_pk_bf16_f32 v41, v44, v45
	buffer_store_dwordx4 v[38:41], v50, s[8:11], 0 offen sc1
	v_add_u32_e32 v50, 0x60000, v37
	s_nop 0
	v_lshlrev_b32_e32 v38, 16, v62
	v_and_b32_e32 v39, 0xffff0000, v62
	v_pk_fma_f32 v[48:49], v[36:37], v[48:49], v[38:39] op_sel_hi:[0,1,1]
	v_lshlrev_b32_e32 v38, 16, v63
	v_and_b32_e32 v39, 0xffff0000, v63
	v_pk_fma_f32 v[42:43], v[36:37], v[42:43], v[38:39] op_sel_hi:[0,1,1]
	v_lshlrev_b32_e32 v38, 16, v64
	v_and_b32_e32 v39, 0xffff0000, v64
	v_pk_fma_f32 v[46:47], v[36:37], v[46:47], v[38:39] op_sel_hi:[0,1,1]
	v_lshlrev_b32_e32 v38, 16, v65
	v_and_b32_e32 v39, 0xffff0000, v65
	v_pk_fma_f32 v[44:45], v[36:37], v[44:45], v[38:39] op_sel_hi:[0,1,1]
	v_cvt_pk_bf16_f32 v38, v48, v49
	v_cvt_pk_bf16_f32 v39, v42, v43
	v_cvt_pk_bf16_f32 v40, v46, v47
	v_cvt_pk_bf16_f32 v41, v44, v45
	buffer_store_dwordx4 v[38:41], v50, s[8:11], 0 offen sc1
	s_nop 1
	v_lshlrev_b32_e32 v38, 16, v32
	v_and_b32_e32 v39, 0xffff0000, v32
	v_lshlrev_b32_e32 v32, 16, v33
	v_and_b32_e32 v33, 0xffff0000, v33
	v_pk_fma_f32 v[40:41], v[36:37], v[42:43], v[32:33] op_sel_hi:[0,1,1]
	v_lshlrev_b32_e32 v32, 16, v34
	v_and_b32_e32 v33, 0xffff0000, v34
	v_pk_fma_f32 v[42:43], v[36:37], v[46:47], v[32:33] op_sel_hi:[0,1,1]
	v_lshlrev_b32_e32 v32, 16, v35
	v_and_b32_e32 v33, 0xffff0000, v35
	v_pk_fma_f32 v[38:39], v[36:37], v[48:49], v[38:39] op_sel_hi:[0,1,1]
	v_pk_fma_f32 v[44:45], v[36:37], v[44:45], v[32:33] op_sel_hi:[0,1,1]
	v_add_u32_e32 v46, 0x70000, v37
	v_cvt_pk_bf16_f32 v32, v38, v39
	v_cvt_pk_bf16_f32 v33, v40, v41
	v_cvt_pk_bf16_f32 v34, v42, v43
	v_cvt_pk_bf16_f32 v35, v44, v45
	buffer_store_dwordx4 v[32:35], v46, s[8:11], 0 offen sc1
	s_nop 1
	v_lshlrev_b32_e32 v32, 16, v28
	v_and_b32_e32 v33, 0xffff0000, v28
	v_lshlrev_b32_e32 v28, 16, v29
	v_and_b32_e32 v29, 0xffff0000, v29
	v_pk_fma_f32 v[34:35], v[36:37], v[40:41], v[28:29] op_sel_hi:[0,1,1]
	v_lshlrev_b32_e32 v28, 16, v30
	v_and_b32_e32 v29, 0xffff0000, v30
	v_pk_fma_f32 v[32:33], v[36:37], v[38:39], v[32:33] op_sel_hi:[0,1,1]
	v_pk_fma_f32 v[38:39], v[36:37], v[42:43], v[28:29] op_sel_hi:[0,1,1]
	v_lshlrev_b32_e32 v28, 16, v31
	v_and_b32_e32 v29, 0xffff0000, v31
	v_pk_fma_f32 v[40:41], v[36:37], v[44:45], v[28:29] op_sel_hi:[0,1,1]
	v_add_u32_e32 v42, 0x80000, v37
	v_cvt_pk_bf16_f32 v28, v32, v33
	v_cvt_pk_bf16_f32 v29, v34, v35
	v_cvt_pk_bf16_f32 v30, v38, v39
	v_cvt_pk_bf16_f32 v31, v40, v41
	buffer_store_dwordx4 v[28:31], v42, s[8:11], 0 offen sc1
	s_nop 1
	v_lshlrev_b32_e32 v28, 16, v24
	v_and_b32_e32 v29, 0xffff0000, v24
	v_lshlrev_b32_e32 v24, 16, v25
	v_and_b32_e32 v25, 0xffff0000, v25
	v_pk_fma_f32 v[30:31], v[36:37], v[34:35], v[24:25] op_sel_hi:[0,1,1]
	v_lshlrev_b32_e32 v24, 16, v26
	v_and_b32_e32 v25, 0xffff0000, v26
	v_pk_fma_f32 v[28:29], v[36:37], v[32:33], v[28:29] op_sel_hi:[0,1,1]
	v_pk_fma_f32 v[32:33], v[36:37], v[38:39], v[24:25] op_sel_hi:[0,1,1]
	v_lshlrev_b32_e32 v24, 16, v27
	v_and_b32_e32 v25, 0xffff0000, v27
	v_pk_fma_f32 v[34:35], v[36:37], v[40:41], v[24:25] op_sel_hi:[0,1,1]
	v_add_u32_e32 v38, 0x90000, v37
	v_cvt_pk_bf16_f32 v24, v28, v29
	v_cvt_pk_bf16_f32 v25, v30, v31
	v_cvt_pk_bf16_f32 v26, v32, v33
	v_cvt_pk_bf16_f32 v27, v34, v35
	buffer_store_dwordx4 v[24:27], v38, s[8:11], 0 offen sc1
	s_nop 1
	v_lshlrev_b32_e32 v24, 16, v20
	v_and_b32_e32 v25, 0xffff0000, v20
	v_lshlrev_b32_e32 v20, 16, v21
	v_and_b32_e32 v21, 0xffff0000, v21
	v_pk_fma_f32 v[26:27], v[36:37], v[30:31], v[20:21] op_sel_hi:[0,1,1]
	v_lshlrev_b32_e32 v20, 16, v22
	v_and_b32_e32 v21, 0xffff0000, v22
	v_pk_fma_f32 v[24:25], v[36:37], v[28:29], v[24:25] op_sel_hi:[0,1,1]
	v_pk_fma_f32 v[28:29], v[36:37], v[32:33], v[20:21] op_sel_hi:[0,1,1]
	v_lshlrev_b32_e32 v20, 16, v23
	v_and_b32_e32 v21, 0xffff0000, v23
	v_pk_fma_f32 v[30:31], v[36:37], v[34:35], v[20:21] op_sel_hi:[0,1,1]
	v_add_u32_e32 v32, 0xa0000, v37
	v_cvt_pk_bf16_f32 v20, v24, v25
	v_cvt_pk_bf16_f32 v21, v26, v27
	v_cvt_pk_bf16_f32 v22, v28, v29
	v_cvt_pk_bf16_f32 v23, v30, v31
	buffer_store_dwordx4 v[20:23], v32, s[8:11], 0 offen sc1
	s_nop 1
	v_lshlrev_b32_e32 v20, 16, v16
	v_and_b32_e32 v21, 0xffff0000, v16
	v_lshlrev_b32_e32 v16, 16, v17
	v_and_b32_e32 v17, 0xffff0000, v17
	v_pk_fma_f32 v[22:23], v[36:37], v[26:27], v[16:17] op_sel_hi:[0,1,1]
	v_lshlrev_b32_e32 v16, 16, v18
	v_and_b32_e32 v17, 0xffff0000, v18
	v_pk_fma_f32 v[20:21], v[36:37], v[24:25], v[20:21] op_sel_hi:[0,1,1]
	v_pk_fma_f32 v[24:25], v[36:37], v[28:29], v[16:17] op_sel_hi:[0,1,1]
	v_lshlrev_b32_e32 v16, 16, v19
	v_and_b32_e32 v17, 0xffff0000, v19
	v_pk_fma_f32 v[26:27], v[36:37], v[30:31], v[16:17] op_sel_hi:[0,1,1]
	v_add_u32_e32 v28, 0xb0000, v37
	v_cvt_pk_bf16_f32 v16, v20, v21
	v_cvt_pk_bf16_f32 v17, v22, v23
	v_cvt_pk_bf16_f32 v18, v24, v25
	v_cvt_pk_bf16_f32 v19, v26, v27
	buffer_store_dwordx4 v[16:19], v28, s[8:11], 0 offen sc1
	s_nop 1
	v_lshlrev_b32_e32 v16, 16, v12
	v_and_b32_e32 v17, 0xffff0000, v12
	v_lshlrev_b32_e32 v12, 16, v13
	v_and_b32_e32 v13, 0xffff0000, v13
	v_pk_fma_f32 v[18:19], v[36:37], v[22:23], v[12:13] op_sel_hi:[0,1,1]
	v_lshlrev_b32_e32 v12, 16, v14
	v_and_b32_e32 v13, 0xffff0000, v14
	v_pk_fma_f32 v[16:17], v[36:37], v[20:21], v[16:17] op_sel_hi:[0,1,1]
	v_pk_fma_f32 v[20:21], v[36:37], v[24:25], v[12:13] op_sel_hi:[0,1,1]
	v_lshlrev_b32_e32 v12, 16, v15
	v_and_b32_e32 v13, 0xffff0000, v15
	v_pk_fma_f32 v[22:23], v[36:37], v[26:27], v[12:13] op_sel_hi:[0,1,1]
	v_add_u32_e32 v24, 0xc0000, v37
	v_cvt_pk_bf16_f32 v12, v16, v17
	v_cvt_pk_bf16_f32 v13, v18, v19
	v_cvt_pk_bf16_f32 v14, v20, v21
	v_cvt_pk_bf16_f32 v15, v22, v23
	buffer_store_dwordx4 v[12:15], v24, s[8:11], 0 offen sc1
	s_nop 1
	v_lshlrev_b32_e32 v12, 16, v8
	v_and_b32_e32 v13, 0xffff0000, v8
	v_lshlrev_b32_e32 v8, 16, v9
	v_and_b32_e32 v9, 0xffff0000, v9
	v_pk_fma_f32 v[14:15], v[36:37], v[18:19], v[8:9] op_sel_hi:[0,1,1]
	v_lshlrev_b32_e32 v8, 16, v10
	v_and_b32_e32 v9, 0xffff0000, v10
	v_pk_fma_f32 v[12:13], v[36:37], v[16:17], v[12:13] op_sel_hi:[0,1,1]
	v_pk_fma_f32 v[16:17], v[36:37], v[20:21], v[8:9] op_sel_hi:[0,1,1]
	v_lshlrev_b32_e32 v8, 16, v11
	v_and_b32_e32 v9, 0xffff0000, v11
	v_pk_fma_f32 v[18:19], v[36:37], v[22:23], v[8:9] op_sel_hi:[0,1,1]
	v_add_u32_e32 v20, 0xd0000, v37
	v_cvt_pk_bf16_f32 v8, v12, v13
	v_cvt_pk_bf16_f32 v9, v14, v15
	v_cvt_pk_bf16_f32 v10, v16, v17
	v_cvt_pk_bf16_f32 v11, v18, v19
	buffer_store_dwordx4 v[8:11], v20, s[8:11], 0 offen sc1
	s_nop 1
	v_lshlrev_b32_e32 v8, 16, v4
	v_and_b32_e32 v9, 0xffff0000, v4
	v_lshlrev_b32_e32 v4, 16, v5
	v_and_b32_e32 v5, 0xffff0000, v5
	v_pk_fma_f32 v[10:11], v[36:37], v[14:15], v[4:5] op_sel_hi:[0,1,1]
	v_lshlrev_b32_e32 v4, 16, v6
	v_and_b32_e32 v5, 0xffff0000, v6
	v_pk_fma_f32 v[8:9], v[36:37], v[12:13], v[8:9] op_sel_hi:[0,1,1]
	v_pk_fma_f32 v[12:13], v[36:37], v[16:17], v[4:5] op_sel_hi:[0,1,1]
	v_lshlrev_b32_e32 v4, 16, v7
	v_and_b32_e32 v5, 0xffff0000, v7
	v_pk_fma_f32 v[14:15], v[36:37], v[18:19], v[4:5] op_sel_hi:[0,1,1]
	v_add_u32_e32 v16, 0xe0000, v37
	v_cvt_pk_bf16_f32 v4, v8, v9
	v_cvt_pk_bf16_f32 v5, v10, v11
	v_cvt_pk_bf16_f32 v6, v12, v13
	v_cvt_pk_bf16_f32 v7, v14, v15
	buffer_store_dwordx4 v[4:7], v16, s[8:11], 0 offen sc1
	s_nop 1
	v_lshlrev_b32_e32 v4, 16, v0
	v_and_b32_e32 v5, 0xffff0000, v0
	v_lshlrev_b32_e32 v0, 16, v1
	v_and_b32_e32 v1, 0xffff0000, v1
	v_pk_fma_f32 v[6:7], v[36:37], v[10:11], v[0:1] op_sel_hi:[0,1,1]
	v_lshlrev_b32_e32 v0, 16, v2
	v_and_b32_e32 v1, 0xffff0000, v2
	v_pk_fma_f32 v[4:5], v[36:37], v[8:9], v[4:5] op_sel_hi:[0,1,1]
	v_pk_fma_f32 v[8:9], v[36:37], v[12:13], v[0:1] op_sel_hi:[0,1,1]
	v_lshlrev_b32_e32 v0, 16, v3
	v_and_b32_e32 v1, 0xffff0000, v3
	v_pk_fma_f32 v[10:11], v[36:37], v[14:15], v[0:1] op_sel_hi:[0,1,1]
	v_add_u32_e32 v12, 0xf0000, v37
	v_cvt_pk_bf16_f32 v0, v4, v5
	v_cvt_pk_bf16_f32 v1, v6, v7
	v_cvt_pk_bf16_f32 v2, v8, v9
	v_cvt_pk_bf16_f32 v3, v10, v11
	buffer_store_dwordx4 v[0:3], v12, s[8:11], 0 offen sc1
